# S5 scan: complex recurrence rewritten as 8 in-place v_fmac per token on the MFMA outputs (was ~21 instr/token with register shuffles)
# speedup vs baseline: 1.1317x; 1.0066x over previous
.LBB0_176:
	s_or_b64 exec, exec, s[4:5]
	s_waitcnt lgkmcnt(0)
	s_barrier
	ds_read_b32 v0, v186
	s_mov_b32 s76, s73
	s_waitcnt lgkmcnt(0)
	v_readfirstlane_b32 s4, v0
	s_cmp_gt_i32 s4, 31
	s_cbranch_scc1 .LBB0_327
	v_mov_b32_e32 v58, v133
	s_lshl_b32 s4, s4, 2
	v_ashrrev_i32_e32 v59, 6, v58
	v_add_u32_e32 v60, s4, v59
	v_and_b32_e32 v61, 31, v60
	s_waitcnt vmcnt(4)
	v_or_b32_e32 v52, s18, v61
	s_waitcnt vmcnt(1)
	v_ashrrev_i32_e32 v53, 31, v52
	v_lshlrev_b64 v[36:37], 12, v[52:53]
	v_and_b32_e32 v62, 15, v58
	v_readlane_b32 s40, v252, 31
	v_lshl_add_u64 v[16:17], s[86:87], 0, v[36:37]
	v_lshl_or_b32 v36, v62, 8, v36
	v_readlane_b32 s42, v252, 33
	v_readlane_b32 s43, v252, 34
	v_bfe_u32 v64, v58, 5, 1
	v_readlane_b32 s41, v252, 32
	v_lshl_add_u64 v[4:5], s[42:43], 0, v[36:37]
	v_and_b32_e32 v2, 48, v58
	v_mov_b32_e32 v3, v1
	v_and_b32_e32 v63, 31, v58
	v_lshlrev_b32_e32 v0, 4, v64
	v_lshl_add_u64 v[18:19], v[4:5], 0, v[2:3]
	v_lshl_add_u64 v[20:21], v[16:17], 0, v[0:1]
	v_lshlrev_b32_e32 v22, 5, v63
	v_mov_b32_e32 v23, v1
	v_lshl_add_u64 v[36:37], s[40:41], 0, v[36:37]
	global_load_dwordx4 v[4:7], v[18:19], off
	global_load_dwordx4 v[8:11], v[18:19], off offset:64
	global_load_dwordx4 v[12:15], v[18:19], off offset:128
	v_lshl_add_u64 v[32:33], v[20:21], 0, v[22:23]
	global_load_dwordx4 v[16:19], v[18:19], off offset:192
	v_lshl_add_u64 v[48:49], v[36:37], 0, v[2:3]
	global_load_dwordx4 v[20:23], v[32:33], off
	global_load_dwordx4 v[24:27], v[32:33], off offset:1024
	global_load_dwordx4 v[28:31], v[32:33], off offset:2048
	s_nop 0
	global_load_dwordx4 v[32:35], v[32:33], off offset:3072
	s_nop 0
	global_load_dwordx4 v[36:39], v[48:49], off
	global_load_dwordx4 v[40:43], v[48:49], off offset:64
	global_load_dwordx4 v[44:47], v[48:49], off offset:128
	s_nop 0
	global_load_dwordx4 v[48:51], v[48:49], off offset:192
	v_and_b32_e32 v3, 63, v58
	v_lshlrev_b32_e32 v65, 13, v59
	v_lshl_or_b32 v56, v52, 4, v62
	v_lshlrev_b64 v[52:53], 9, v[52:53]
	v_readlane_b32 s44, v252, 35
	v_readlane_b32 s45, v252, 36
	v_mov_b32_e32 v55, v1
	v_lshlrev_b32_e32 v54, 3, v63
	v_lshl_or_b32 v104, v3, 4, v65
	v_ashrrev_i32_e32 v57, 31, v56
	v_lshl_add_u64 v[52:53], s[84:85], 0, v[52:53]
	v_lshl_add_u64 v[56:57], v[56:57], 2, s[44:45]
	v_lshl_add_u64 v[52:53], v[52:53], 0, v[54:55]
	global_load_dwordx2 v[78:79], v[52:53], off
	global_load_dwordx2 v[80:81], v[52:53], off offset:256
	s_waitcnt vmcnt(63) expcnt(7) lgkmcnt(15)
	s_barrier
	global_load_dword v82, v[56:57], off
	v_readlane_b32 s6, v253, 15
	v_readlane_b32 s7, v253, 16
	s_movk_i32 s5, 0x4000
	v_readlane_b32 s46, v252, 37
	v_readlane_b32 s47, v252, 38
	v_readlane_b32 s48, v252, 39
	v_readlane_b32 s49, v252, 40
	v_readlane_b32 s50, v252, 41
	v_readlane_b32 s51, v252, 42
	v_readlane_b32 s52, v252, 43
	v_readlane_b32 s53, v252, 44
	v_readlane_b32 s54, v252, 45
	v_readlane_b32 s55, v252, 46
	s_waitcnt vmcnt(10)
	ds_write_b128 v104, v[20:23] offset:34816
	s_waitcnt vmcnt(8)
	ds_write_b128 v104, v[28:31] offset:35840
	ds_write_b128 v104, v[24:27] offset:36864
	s_waitcnt vmcnt(7)
	ds_write_b128 v104, v[32:35] offset:37888
	v_xor_b32_e32 v3, 0x80000000, v4
	v_xor_b32_e32 v5, 0x80000000, v5
	v_xor_b32_e32 v6, 0x80000000, v6
	v_xor_b32_e32 v7, 0x80000000, v7
	v_xor_b32_e32 v16, 0x80000000, v16
	v_xor_b32_e32 v8, 0x80000000, v8
	v_xor_b32_e32 v9, 0x80000000, v9
	v_xor_b32_e32 v10, 0x80000000, v10
	v_xor_b32_e32 v11, 0x80000000, v11
	v_xor_b32_e32 v12, 0x80000000, v12
	v_xor_b32_e32 v13, 0x80000000, v13
	v_xor_b32_e32 v14, 0x80000000, v14
	v_xor_b32_e32 v15, 0x80000000, v15
	v_xor_b32_e32 v17, 0x80000000, v17
	v_xor_b32_e32 v18, 0x80000000, v18
	v_xor_b32_e32 v19, 0x80000000, v19
	s_waitcnt vmcnt(6)
	v_cvt_pk_bf16_f32 v4, v36, v3
	v_cvt_pk_bf16_f32 v5, v37, v5
	v_cvt_pk_bf16_f32 v6, v38, v6
	v_cvt_pk_bf16_f32 v7, v39, v7
	s_waitcnt vmcnt(3)
	v_cvt_pk_bf16_f32 v16, v48, v16
	v_cvt_pk_bf16_f32 v8, v40, v8
	v_cvt_pk_bf16_f32 v9, v41, v9
	v_cvt_pk_bf16_f32 v10, v42, v10
	v_cvt_pk_bf16_f32 v11, v43, v11
	v_cvt_pk_bf16_f32 v12, v44, v12
	v_cvt_pk_bf16_f32 v13, v45, v13
	v_cvt_pk_bf16_f32 v14, v46, v14
	v_cvt_pk_bf16_f32 v15, v47, v15
	v_cvt_pk_bf16_f32 v17, v49, v17
	v_cvt_pk_bf16_f32 v18, v50, v18
	v_cvt_pk_bf16_f32 v19, v51, v19
	ds_write_b128 v104, v[4:7] offset:38912
	ds_write_b128 v104, v[8:11] offset:39936
	ds_write_b128 v104, v[12:15] offset:40960
	ds_write_b128 v104, v[16:19] offset:41984
	v_lshrrev_b32_e32 v3, 2, v58
	v_ashrrev_i32_e32 v16, 4, v60
	v_bfi_b32 v6, -2, v16, v3
	v_and_b32_e32 v4, 3, v58
	v_lshrrev_b32_e32 v5, 1, v58
	v_ashrrev_i32_e32 v7, 31, v6
	v_and_or_b32 v5, v5, 12, v4
	v_lshlrev_b64 v[6:7], 22, v[6:7]
	v_lshl_add_u64 v[6:7], s[6:7], 0, v[6:7]
	v_lshlrev_b32_e32 v8, 10, v5
	v_mov_b32_e32 v9, v1
	v_and_b32_e32 v4, -2, v16
	v_lshl_add_u64 v[6:7], v[6:7], 0, v[8:9]
	v_lshlrev_b32_e32 v8, 5, v61
	v_lshl_add_u64 v[6:7], v[6:7], 0, v[8:9]
	v_ashrrev_i32_e32 v5, 31, v4
	v_lshl_add_u64 v[84:85], v[6:7], 0, v[0:1]
	v_lshlrev_b64 v[4:5], 22, v[4:5]
	v_lshlrev_b32_e32 v0, 8, v58
	v_lshl_add_u64 v[6:7], s[6:7], 0, v[4:5]
	v_and_b32_e32 v10, 0x3000, v0
	v_mov_b32_e32 v11, v1
	v_lshl_add_u64 v[6:7], v[6:7], 0, v[10:11]
	v_lshl_add_u64 v[6:7], v[6:7], 0, v[8:9]
	v_lshlrev_b32_e32 v0, 1, v62
	v_lshl_add_u64 v[86:87], v[6:7], 0, v[0:1]
	v_add_co_u32_e32 v6, vcc, s5, v84
	s_waitcnt lgkmcnt(0)
	s_nop 0
	v_addc_co_u32_e32 v7, vcc, 0, v85, vcc
	v_add_co_u32_e32 v8, vcc, s5, v86
	s_barrier
	s_nop 0
	v_addc_co_u32_e32 v9, vcc, 0, v87, vcc
	v_add_co_u32_e32 v12, vcc, s70, v86
	global_load_ushort v3, v[86:87], off
	global_load_ushort v11, v[86:87], off offset:1024
	global_load_ushort v17, v[86:87], off offset:2048
	global_load_ushort v18, v[8:9], off
	global_load_ushort v19, v[8:9], off offset:1024
	global_load_ushort v20, v[86:87], off offset:3072
	v_addc_co_u32_e32 v13, vcc, 0, v87, vcc
	s_mov_b32 s5, 0x404000
	v_add_co_u32_e32 v14, vcc, s5, v86
	s_mov_b32 s5, -2
	s_nop 0
	v_addc_co_u32_e32 v15, vcc, 0, v87, vcc
	global_load_ushort v21, v[8:9], off offset:2048
	s_nop 0
	global_load_ushort v8, v[8:9], off offset:3072
	s_nop 0
	global_load_ushort v9, v[12:13], off
	global_load_ushort v22, v[12:13], off offset:1024
	global_load_ushort v23, v[14:15], off
	global_load_ushort v24, v[14:15], off offset:1024
	global_load_ushort v25, v[12:13], off offset:2048
	s_nop 0
	global_load_ushort v12, v[12:13], off offset:3072
	s_nop 0
	global_load_ushort v13, v[14:15], off offset:2048
	s_nop 0
	global_load_ushort v14, v[14:15], off offset:3072
	s_nop 0
	global_load_dwordx4 v[74:77], v[6:7], off
	global_load_dwordx4 v[50:53], v[84:85], off
	s_waitcnt vmcnt(20)
	v_pk_mov_b32 v[88:89], v[78:79], v[78:79] op_sel:[1,0]
	s_waitcnt vmcnt(19)
	v_pk_mov_b32 v[90:91], v[80:81], v[80:81] op_sel:[1,0]
	s_waitcnt vmcnt(16)
	v_perm_b32 v115, v11, v3, s69
	v_lshl_add_u32 v3, v59, 9, v65
	s_waitcnt vmcnt(13)
	v_perm_b32 v111, v19, v18, s69
	s_waitcnt vmcnt(12)
	v_perm_b32 v114, v20, v17, s69
	s_waitcnt vmcnt(10)
	v_perm_b32 v110, v8, v21, s69
	s_waitcnt vmcnt(8)
	v_perm_b32 v113, v22, v9, s69
	s_waitcnt vmcnt(6)
	v_perm_b32 v109, v24, v23, s69
	s_waitcnt vmcnt(4)
	v_perm_b32 v112, v12, v25, s69
	s_waitcnt vmcnt(2)
	v_perm_b32 v108, v14, v13, s69
	s_setprio 1
	v_mul_u32_u24_e32 v6, 0x440, v64
	v_lshl_add_u32 v6, v6, 2, v3
	v_lshl_or_b32 v105, v63, 2, v6
	v_mul_u32_u24_e32 v6, 0x44, v62
	v_or_b32_e32 v7, v3, v2
	v_lshlrev_b32_e32 v6, 2, v6
	v_add_u32_e32 v106, v7, v6
	v_add3_u32 v107, v3, v6, v2
	v_or_b32_e32 v2, 1, v16
	v_add_u16_e32 v6, s4, v59
	v_ashrrev_i32_e32 v3, 31, v2
	v_and_b32_e32 v6, 31, v6
	v_lshlrev_b64 v[2:3], 22, v[2:3]
	v_lshlrev_b32_e32 v6, 5, v6
	v_or3_b32 v2, v2, v10, v6
	v_or3_b32 v4, v4, v10, v6
	v_mov_b32_e32 v96, 0
	v_mov_b32_e32 v83, v82
	v_lshl_add_u64 v[92:93], s[92:93], 0, v[2:3]
	v_lshl_add_u64 v[94:95], s[92:93], 0, v[4:5]
	v_mov_b32_e32 v97, v96
	v_mov_b32_e32 v98, v96
	v_mov_b32_e32 v99, v96
	s_waitcnt vmcnt(0)
	v_mov_b32_e32 v236, 0
	v_mov_b32_e32 v237, 0
	v_mov_b32_e32 v238, 0
	v_mov_b32_e32 v239, 0
	v_xor_b32_e32 v240, 0x80000000, v79
	v_xor_b32_e32 v241, 0x80000000, v81
.LBB0_178:
	s_add_i32 s4, s5, 2
	s_min_u32 s6, s4, 0xfd
	s_lshl_b32 s6, s6, 14
	s_add_i32 s96, s6, 0x8000
	v_lshl_add_u64 v[2:3], v[84:85], 0, s[96:97]
	global_load_dwordx4 v[66:69], v[2:3], off
	v_lshl_add_u64 v[2:3], v[86:87], 0, s[96:97]
	global_load_ushort v220, v[2:3], off
	global_load_ushort v221, v[2:3], off offset:1024
	v_add_u32_e32 v124, 0xa00, v105
	v_add_u32_e32 v125, 0xc00, v105
	v_add_u32_e32 v126, 0xe00, v105
	v_add_u32_e32 v127, 0x9800, v104
	v_add_u32_e32 v128, 0x9c00, v104
	v_add_u32_e32 v129, 0xa000, v104
	v_lshl_add_u64 v[102:103], v[94:95], 0, v[0:1]
	v_lshl_add_u64 v[100:101], v[92:93], 0, v[0:1]
	s_add_i32 s5, s5, 3
	s_min_u32 s5, s5, 0xfd
	s_lshl_b32 s5, s5, 14
	s_add_i32 s96, s5, 0x8000
	v_lshl_add_u64 v[92:93], v[92:93], 0, s[22:23]
	v_lshl_add_u64 v[94:95], v[94:95], 0, s[22:23]
	s_cmpk_lt_u32 s4, 0xfe
	s_mov_b32 s5, s4
	global_load_ushort v222, v[2:3], off offset:2048
	global_load_ushort v223, v[2:3], off offset:3072
	v_add_co_u32_e32 v2, vcc, s70, v2
	s_nop 1
	v_addc_co_u32_e32 v3, vcc, 0, v3, vcc
	global_load_ushort v224, v[2:3], off
	global_load_ushort v225, v[2:3], off offset:1024
	global_load_ushort v226, v[2:3], off offset:2048
	s_nop 0
	global_load_ushort v227, v[2:3], off offset:3072
	ds_read_b128 v[18:21], v104 offset:35840
	s_waitcnt lgkmcnt(0)
	v_mfma_f32_32x32x16_bf16 v[34:49], v[50:53], v[18:21], 0
	ds_read_b128 v[18:21], v104 offset:36864
	ds_read_b128 v[54:57], v104 offset:37888
	ds_read_b128 v[2:5], v104 offset:34816
	s_waitcnt lgkmcnt(0)
	v_mfma_f32_32x32x16_bf16 v[2:17], v[50:53], v[2:5], 0
	v_mfma_f32_32x32x16_bf16 v[18:33], v[50:53], v[18:21], 0
	v_mfma_f32_32x32x16_bf16 v[50:65], v[50:53], v[54:57], 0
	s_nop 10
	v_add_u32_e32 v98, 0x400, v105
	v_add_u32_e32 v99, 0x800, v105
	v_fmac_f32_e32 v2, v240, v237
	v_fmac_f32_e32 v34, v79, v236
	v_fmac_f32_e32 v18, v241, v239
	v_fmac_f32_e32 v50, v81, v238
	v_fmac_f32_e32 v2, v78, v236
	v_fmac_f32_e32 v34, v78, v237
	v_fmac_f32_e32 v18, v80, v238
	v_fmac_f32_e32 v50, v80, v239
	v_cvt_pk_bf16_f32 v242, v2, v34
	v_cvt_pk_bf16_f32 v243, v18, v50
	ds_write2_b32 v105, v242, v243 offset1:32
	v_fmac_f32_e32 v3, v240, v34
	v_fmac_f32_e32 v35, v79, v2
	v_fmac_f32_e32 v19, v241, v50
	v_fmac_f32_e32 v51, v81, v18
	v_fmac_f32_e32 v3, v78, v2
	v_fmac_f32_e32 v35, v78, v34
	v_fmac_f32_e32 v19, v80, v18
	v_fmac_f32_e32 v51, v80, v50
	v_cvt_pk_bf16_f32 v244, v3, v35
	v_cvt_pk_bf16_f32 v245, v19, v51
	ds_write2_b32 v105, v244, v245 offset0:68 offset1:100
	v_fmac_f32_e32 v4, v240, v35
	v_fmac_f32_e32 v36, v79, v3
	v_fmac_f32_e32 v20, v241, v51
	v_fmac_f32_e32 v52, v81, v19
	v_fmac_f32_e32 v4, v78, v3
	v_fmac_f32_e32 v36, v78, v35
	v_fmac_f32_e32 v20, v80, v19
	v_fmac_f32_e32 v52, v80, v51
	v_cvt_pk_bf16_f32 v242, v4, v36
	v_cvt_pk_bf16_f32 v243, v20, v52
	ds_write2_b32 v105, v242, v243 offset0:136 offset1:168
	v_fmac_f32_e32 v5, v240, v36
	v_fmac_f32_e32 v37, v79, v4
	v_fmac_f32_e32 v21, v241, v52
	v_fmac_f32_e32 v53, v81, v20
	v_fmac_f32_e32 v5, v78, v4
	v_fmac_f32_e32 v37, v78, v36
	v_fmac_f32_e32 v21, v80, v20
	v_fmac_f32_e32 v53, v80, v52
	v_cvt_pk_bf16_f32 v244, v5, v37
	v_cvt_pk_bf16_f32 v245, v21, v53
	ds_write2_b32 v105, v244, v245 offset0:204 offset1:236
	v_fmac_f32_e32 v6, v240, v37
	v_fmac_f32_e32 v38, v79, v5
	v_fmac_f32_e32 v22, v241, v53
	v_fmac_f32_e32 v54, v81, v21
	v_fmac_f32_e32 v6, v78, v5
	v_fmac_f32_e32 v38, v78, v37
	v_fmac_f32_e32 v22, v80, v21
	v_fmac_f32_e32 v54, v80, v53
	v_cvt_pk_bf16_f32 v242, v6, v38
	v_cvt_pk_bf16_f32 v243, v22, v54
	ds_write2_b32 v98, v242, v243 offset0:16 offset1:48
	v_fmac_f32_e32 v7, v240, v38
	v_fmac_f32_e32 v39, v79, v6
	v_fmac_f32_e32 v23, v241, v54
	v_fmac_f32_e32 v55, v81, v22
	v_fmac_f32_e32 v7, v78, v6
	v_fmac_f32_e32 v39, v78, v38
	v_fmac_f32_e32 v23, v80, v22
	v_fmac_f32_e32 v55, v80, v54
	v_cvt_pk_bf16_f32 v244, v7, v39
	v_cvt_pk_bf16_f32 v245, v23, v55
	ds_write2_b32 v98, v244, v245 offset0:84 offset1:116
	v_fmac_f32_e32 v8, v240, v39
	v_fmac_f32_e32 v40, v79, v7
	v_fmac_f32_e32 v24, v241, v55
	v_fmac_f32_e32 v56, v81, v23
	v_fmac_f32_e32 v8, v78, v7
	v_fmac_f32_e32 v40, v78, v39
	v_fmac_f32_e32 v24, v80, v23
	v_fmac_f32_e32 v56, v80, v55
	v_cvt_pk_bf16_f32 v242, v8, v40
	v_cvt_pk_bf16_f32 v243, v24, v56
	ds_write2_b32 v98, v242, v243 offset0:152 offset1:184
	v_fmac_f32_e32 v9, v240, v40
	v_fmac_f32_e32 v41, v79, v8
	v_fmac_f32_e32 v25, v241, v56
	v_fmac_f32_e32 v57, v81, v24
	v_fmac_f32_e32 v9, v78, v8
	v_fmac_f32_e32 v41, v78, v40
	v_fmac_f32_e32 v25, v80, v24
	v_fmac_f32_e32 v57, v80, v56
	v_cvt_pk_bf16_f32 v244, v9, v41
	v_cvt_pk_bf16_f32 v245, v25, v57
	ds_write2_b32 v98, v244, v245 offset0:220 offset1:252
	v_fmac_f32_e32 v10, v240, v41
	v_fmac_f32_e32 v42, v79, v9
	v_fmac_f32_e32 v26, v241, v57
	v_fmac_f32_e32 v58, v81, v25
	v_fmac_f32_e32 v10, v78, v9
	v_fmac_f32_e32 v42, v78, v41
	v_fmac_f32_e32 v26, v80, v25
	v_fmac_f32_e32 v58, v80, v57
	v_cvt_pk_bf16_f32 v242, v10, v42
	v_cvt_pk_bf16_f32 v243, v26, v58
	ds_write2_b32 v99, v242, v243 offset0:32 offset1:64
	v_fmac_f32_e32 v11, v240, v42
	v_fmac_f32_e32 v43, v79, v10
	v_fmac_f32_e32 v27, v241, v58
	v_fmac_f32_e32 v59, v81, v26
	v_fmac_f32_e32 v11, v78, v10
	v_fmac_f32_e32 v43, v78, v42
	v_fmac_f32_e32 v27, v80, v26
	v_fmac_f32_e32 v59, v80, v58
	v_cvt_pk_bf16_f32 v244, v11, v43
	v_cvt_pk_bf16_f32 v245, v27, v59
	ds_write2_b32 v99, v244, v245 offset0:100 offset1:132
	v_fmac_f32_e32 v12, v240, v43
	v_fmac_f32_e32 v44, v79, v11
	v_fmac_f32_e32 v28, v241, v59
	v_fmac_f32_e32 v60, v81, v27
	v_fmac_f32_e32 v12, v78, v11
	v_fmac_f32_e32 v44, v78, v43
	v_fmac_f32_e32 v28, v80, v27
	v_fmac_f32_e32 v60, v80, v59
	v_cvt_pk_bf16_f32 v242, v12, v44
	v_cvt_pk_bf16_f32 v243, v28, v60
	ds_write2_b32 v99, v242, v243 offset0:168 offset1:200
	v_fmac_f32_e32 v13, v240, v44
	v_fmac_f32_e32 v45, v79, v12
	v_fmac_f32_e32 v29, v241, v60
	v_fmac_f32_e32 v61, v81, v28
	v_fmac_f32_e32 v13, v78, v12
	v_fmac_f32_e32 v45, v78, v44
	v_fmac_f32_e32 v29, v80, v28
	v_fmac_f32_e32 v61, v80, v60
	v_cvt_pk_bf16_f32 v244, v13, v45
	v_cvt_pk_bf16_f32 v245, v29, v61
	ds_write2_b32 v124, v244, v245 offset0:108 offset1:140
	v_fmac_f32_e32 v14, v240, v45
	v_fmac_f32_e32 v46, v79, v13
	v_fmac_f32_e32 v30, v241, v61
	v_fmac_f32_e32 v62, v81, v29
	v_fmac_f32_e32 v14, v78, v13
	v_fmac_f32_e32 v46, v78, v45
	v_fmac_f32_e32 v30, v80, v29
	v_fmac_f32_e32 v62, v80, v61
	v_cvt_pk_bf16_f32 v242, v14, v46
	v_cvt_pk_bf16_f32 v243, v30, v62
	ds_write2_b32 v125, v242, v243 offset0:48 offset1:80
	v_fmac_f32_e32 v15, v240, v46
	v_fmac_f32_e32 v47, v79, v14
	v_fmac_f32_e32 v31, v241, v62
	v_fmac_f32_e32 v63, v81, v30
	v_fmac_f32_e32 v15, v78, v14
	v_fmac_f32_e32 v47, v78, v46
	v_fmac_f32_e32 v31, v80, v30
	v_fmac_f32_e32 v63, v80, v62
	v_cvt_pk_bf16_f32 v244, v15, v47
	v_cvt_pk_bf16_f32 v245, v31, v63
	ds_write2_b32 v125, v244, v245 offset0:116 offset1:148
	v_fmac_f32_e32 v16, v240, v47
	v_fmac_f32_e32 v48, v79, v15
	v_fmac_f32_e32 v32, v241, v63
	v_fmac_f32_e32 v64, v81, v31
	v_fmac_f32_e32 v16, v78, v15
	v_fmac_f32_e32 v48, v78, v47
	v_fmac_f32_e32 v32, v80, v31
	v_fmac_f32_e32 v64, v80, v63
	v_cvt_pk_bf16_f32 v242, v16, v48
	v_cvt_pk_bf16_f32 v243, v32, v64
	ds_write2_b32 v125, v242, v243 offset0:184 offset1:216
	v_fmac_f32_e32 v17, v240, v48
	v_fmac_f32_e32 v49, v79, v16
	v_fmac_f32_e32 v33, v241, v64
	v_fmac_f32_e32 v65, v81, v32
	v_fmac_f32_e32 v17, v78, v16
	v_fmac_f32_e32 v49, v78, v48
	v_fmac_f32_e32 v33, v80, v32
	v_fmac_f32_e32 v65, v80, v64
	v_cvt_pk_bf16_f32 v244, v17, v49
	v_cvt_pk_bf16_f32 v245, v33, v65
	ds_write2_b32 v126, v244, v245 offset0:124 offset1:156
	v_mov_b32_e32 v236, v17
	v_mov_b32_e32 v237, v49
	v_mov_b32_e32 v238, v33
	v_mov_b32_e32 v239, v65
	s_waitcnt lgkmcnt(0)
	s_barrier
	ds_read_b128 v[12:15], v106
	ds_read_b64 v[4:5], v104 offset:38912
	ds_read_b32 v2, v104 offset:38912
	ds_read2_b64 v[8:11], v127 offset0:1 offset1:128
	ds_read_b128 v[20:23], v106 offset:64
	v_lshl_add_u64 v[30:31], v[84:85], 0, s[96:97]
	s_waitcnt lgkmcnt(1)
	v_mov_b32_e32 v6, v8
	v_mov_b32_e32 v7, v9
	v_mov_b32_e32 v24, v10
	v_mov_b32_e32 v25, v11
	v_mfma_f32_16x16x32_bf16 v[16:19], v[12:15], v[4:7], 0
	ds_read2_b64 v[12:15], v128 offset0:1 offset1:128
	v_and_b32_e32 v7, 0xffff0000, v115
	v_lshlrev_b32_e32 v6, 16, v115
	v_lshl_add_u64 v[28:29], v[86:87], 0, s[96:97]
	s_waitcnt vmcnt(0)
	v_perm_b32 v116, v221, v220, s69
	v_perm_b32 v117, v223, v222, s69
	v_perm_b32 v118, v225, v224, s69
	v_perm_b32 v119, v227, v226, s69
	v_mov_b32_e32 v115, v116
	s_waitcnt lgkmcnt(0)
	v_mov_b32_e32 v26, v12
	v_mov_b32_e32 v27, v13
	v_mov_b32_e32 v32, v14
	v_mov_b32_e32 v33, v15
	v_mfma_f32_16x16x32_bf16 v[20:23], v[20:23], v[24:27], v[16:19]
	ds_read_b128 v[24:27], v106 offset:128
	s_nop 1
	ds_read2_b64 v[16:19], v129 offset0:1 offset1:128
	s_waitcnt lgkmcnt(0)
	v_mov_b32_e32 v34, v16
	v_mov_b32_e32 v35, v17
	s_nop 1
	v_mfma_f32_16x16x32_bf16 v[24:27], v[24:27], v[32:35], v[20:23]
	ds_read_b128 v[32:35], v106 offset:192
	s_nop 1
	ds_read_b64 v[22:23], v104 offset:41992
	v_mov_b32_e32 v20, v18
	v_mov_b32_e32 v21, v19
	s_waitcnt lgkmcnt(0)
	s_nop 0
	v_mfma_f32_16x16x32_bf16 v[24:27], v[32:35], v[20:23], v[24:27]
	s_nop 7
	v_pk_fma_f32 v[20:21], v[82:83], v[6:7], v[24:25]
	s_nop 0
	v_pk_mul_f32 v[6:7], v[20:21], s[28:29] op_sel_hi:[1,0]
	v_mul_f32_e32 v3, 0.5, v20
	v_pk_mul_f32 v[6:7], v[20:21], v[6:7]
	s_nop 0
	v_pk_fma_f32 v[6:7], v[20:21], v[6:7], v[20:21]
	s_nop 0
	v_pk_mul_f32 v[24:25], v[6:7], s[20:21] op_sel_hi:[1,0]
	s_nop 0
	v_mul_f32_e64 v4, |v24|, -2.0
	v_mul_f32_e32 v4, 0x3fb8aa3b, v4
	v_exp_f32_e32 v4, v4
	v_cmp_gt_f32_e64 s[38:39], 0, v25
	v_sub_f32_e32 v6, 1.0, v4
	v_add_f32_e32 v4, 1.0, v4
	v_div_scale_f32 v7, s[6:7], v4, v4, v6
	v_rcp_f32_e32 v10, v7
	s_nop 0
	v_fma_f32 v14, -v7, v10, 1.0
	v_fmac_f32_e32 v10, v14, v10
	v_div_scale_f32 v14, vcc, v6, v4, v6
	v_mul_f32_e32 v18, v14, v10
	v_fma_f32 v20, -v7, v18, v14
	v_fmac_f32_e32 v18, v20, v10
	v_fma_f32 v7, -v7, v18, v14
	v_div_fmas_f32 v7, v7, v10, v18
	v_div_fixup_f32 v4, v7, v4, v6
	v_cmp_gt_f32_e32 vcc, 0, v24
	s_nop 1
	v_cndmask_b32_e64 v4, v4, -v4, vcc
	v_add_f32_e32 v4, 1.0, v4
	v_mul_f32_e32 v3, v3, v4
	v_mul_f32_e64 v4, |v25|, -2.0
	v_mul_f32_e32 v4, 0x3fb8aa3b, v4
	v_exp_f32_e32 v4, v4
	v_add_co_u32_e32 v6, vcc, s71, v102
	v_cvt_pk_bf16_f32 v3, v3, s0
	v_sub_f32_e32 v10, 1.0, v4
	v_add_f32_e32 v4, 1.0, v4
	v_div_scale_f32 v14, s[6:7], v4, v4, v10
	v_rcp_f32_e32 v18, v14
	v_addc_co_u32_e32 v7, vcc, 0, v103, vcc
	global_store_short v[6:7], v3, off
	v_fma_f32 v20, -v14, v18, 1.0
	v_fmac_f32_e32 v18, v20, v18
	v_div_scale_f32 v20, vcc, v10, v4, v10
	v_mul_f32_e32 v3, 0.5, v21
	v_mul_f32_e32 v21, v20, v18
	v_fma_f32 v24, -v14, v21, v20
	v_fmac_f32_e32 v21, v24, v18
	v_fma_f32 v14, -v14, v21, v20
	v_div_fmas_f32 v14, v14, v18, v21
	v_and_b32_e32 v21, 0xffff0000, v114
	v_lshlrev_b32_e32 v20, 16, v114
	v_pk_fma_f32 v[20:21], v[82:83], v[20:21], v[26:27]
	v_div_fixup_f32 v4, v14, v4, v10
	v_pk_mul_f32 v[24:25], v[20:21], s[28:29] op_sel_hi:[1,0]
	v_cndmask_b32_e64 v4, v4, -v4, s[38:39]
	v_pk_mul_f32 v[24:25], v[20:21], v[24:25]
	v_add_f32_e32 v4, 1.0, v4
	v_pk_fma_f32 v[24:25], v[20:21], v[24:25], v[20:21]
	v_mul_f32_e32 v3, v3, v4
	v_pk_mul_f32 v[24:25], v[24:25], s[20:21] op_sel_hi:[1,0]
	v_cvt_pk_bf16_f32 v3, v3, s0
	v_mul_f32_e64 v4, |v24|, -2.0
	v_mul_f32_e32 v4, 0x3fb8aa3b, v4
	v_exp_f32_e32 v4, v4
	global_store_short v[6:7], v3, off offset:1024
	v_mul_f32_e32 v3, 0.5, v20
	v_cmp_gt_f32_e64 s[38:39], 0, v25
	v_sub_f32_e32 v10, 1.0, v4
	v_add_f32_e32 v4, 1.0, v4
	v_div_scale_f32 v14, s[6:7], v4, v4, v10
	v_rcp_f32_e32 v18, v14
	v_mov_b32_e32 v114, v117
	v_fma_f32 v20, -v14, v18, 1.0
	v_fmac_f32_e32 v18, v20, v18
	v_div_scale_f32 v20, vcc, v10, v4, v10
	v_mul_f32_e32 v26, v20, v18
	v_fma_f32 v27, -v14, v26, v20
	v_fmac_f32_e32 v26, v27, v18
	v_fma_f32 v14, -v14, v26, v20
	v_div_fmas_f32 v14, v14, v18, v26
	v_div_fixup_f32 v4, v14, v4, v10
	v_cmp_gt_f32_e32 vcc, 0, v24
	s_nop 1
	v_cndmask_b32_e64 v4, v4, -v4, vcc
	v_add_f32_e32 v4, 1.0, v4
	v_mul_f32_e32 v3, v3, v4
	v_mul_f32_e64 v4, |v25|, -2.0
	v_mul_f32_e32 v4, 0x3fb8aa3b, v4
	v_exp_f32_e32 v4, v4
	v_cvt_pk_bf16_f32 v3, v3, s0
	global_store_short v[6:7], v3, off offset:2048
	v_mul_f32_e32 v3, 0.5, v21
	v_sub_f32_e32 v10, 1.0, v4
	v_add_f32_e32 v4, 1.0, v4
	v_div_scale_f32 v14, s[6:7], v4, v4, v10
	v_rcp_f32_e32 v18, v14
	s_nop 0
	v_fma_f32 v20, -v14, v18, 1.0
	v_fmac_f32_e32 v18, v20, v18
	v_div_scale_f32 v20, vcc, v10, v4, v10
	v_mul_f32_e32 v21, v20, v18
	v_fma_f32 v24, -v14, v21, v20
	v_fmac_f32_e32 v21, v24, v18
	v_fma_f32 v14, -v14, v21, v20
	ds_read_b128 v[24:27], v107 offset:4352
	v_div_fmas_f32 v14, v14, v18, v21
	v_div_fixup_f32 v4, v14, v4, v10
	v_cndmask_b32_e64 v4, v4, -v4, s[38:39]
	v_add_f32_e32 v4, 1.0, v4
	v_mul_f32_e32 v3, v3, v4
	v_cvt_pk_bf16_f32 v3, v3, s0
	global_store_short v[6:7], v3, off offset:3072
	v_mov_b32_e32 v3, v5
	v_mov_b32_e32 v4, v8
	v_mov_b32_e32 v5, v9
	ds_read_b128 v[6:9], v107 offset:4416
	ds_read_b32 v10, v104 offset:39936
	s_waitcnt lgkmcnt(2)
	v_mfma_f32_16x16x32_bf16 v[2:5], v[24:27], v[2:5], 0
	v_mov_b32_e32 v21, v19
	s_waitcnt lgkmcnt(0)
	v_mfma_f32_16x16x32_bf16 v[2:5], v[6:9], v[10:13], v[2:5]
	ds_read_b128 v[6:9], v107 offset:4480
	ds_read_b32 v10, v104 offset:40960
	v_mov_b32_e32 v11, v15
	v_mov_b32_e32 v12, v16
	v_mov_b32_e32 v13, v17
	s_waitcnt lgkmcnt(0)
	s_nop 0
	v_mfma_f32_16x16x32_bf16 v[2:5], v[6:9], v[10:13], v[2:5]
	ds_read_b128 v[6:9], v107 offset:4544
	ds_read_b32 v20, v104 offset:41984
	s_waitcnt lgkmcnt(0)
	v_mfma_f32_16x16x32_bf16 v[2:5], v[6:9], v[20:23], v[2:5]
	v_and_b32_e32 v7, 0xffff0000, v113
	v_lshlrev_b32_e32 v6, 16, v113
	s_nop 5
	v_pk_fma_f32 v[6:7], v[82:83], v[6:7], v[2:3]
	s_nop 0
	v_pk_mul_f32 v[2:3], v[6:7], s[28:29] op_sel_hi:[1,0]
	v_mul_f32_e32 v10, 0.5, v6
	v_pk_mul_f32 v[2:3], v[6:7], v[2:3]
	s_nop 0
	v_pk_fma_f32 v[2:3], v[6:7], v[2:3], v[6:7]
	s_nop 0
	v_pk_mul_f32 v[8:9], v[2:3], s[20:21] op_sel_hi:[1,0]
	s_nop 0
	v_mul_f32_e64 v2, |v8|, -2.0
	v_mul_f32_e32 v2, 0x3fb8aa3b, v2
	v_exp_f32_e32 v2, v2
	v_cmp_gt_f32_e64 s[38:39], 0, v9
	v_sub_f32_e32 v3, 1.0, v2
	v_add_f32_e32 v2, 1.0, v2
	v_div_scale_f32 v6, s[6:7], v2, v2, v3
	v_rcp_f32_e32 v11, v6
	s_nop 0
	v_fma_f32 v12, -v6, v11, 1.0
	v_fmac_f32_e32 v11, v12, v11
	v_div_scale_f32 v12, vcc, v3, v2, v3
	v_mul_f32_e32 v13, v12, v11
	v_fma_f32 v14, -v6, v13, v12
	v_fmac_f32_e32 v13, v14, v11
	v_fma_f32 v6, -v6, v13, v12
	v_div_fmas_f32 v6, v6, v11, v13
	v_div_fixup_f32 v2, v6, v2, v3
	v_cmp_gt_f32_e32 vcc, 0, v8
	s_nop 1
	v_cndmask_b32_e64 v2, v2, -v2, vcc
	v_add_f32_e32 v2, 1.0, v2
	v_mul_f32_e32 v2, v10, v2
	v_cvt_pk_bf16_f32 v6, v2, s0
	v_add_co_u32_e32 v2, vcc, s71, v100
	s_nop 1
	v_addc_co_u32_e32 v3, vcc, 0, v101, vcc
	global_store_short v[2:3], v6, off
	v_mul_f32_e32 v6, 0.5, v7
	v_mul_f32_e64 v7, |v9|, -2.0
	v_mul_f32_e32 v7, 0x3fb8aa3b, v7
	v_exp_f32_e32 v7, v7
	s_nop 0
	v_sub_f32_e32 v8, 1.0, v7
	v_add_f32_e32 v7, 1.0, v7
	v_div_scale_f32 v9, s[6:7], v7, v7, v8
	v_rcp_f32_e32 v10, v9
	s_nop 0
	v_fma_f32 v11, -v9, v10, 1.0
	v_fmac_f32_e32 v10, v11, v10
	v_div_scale_f32 v11, vcc, v8, v7, v8
	v_mul_f32_e32 v12, v11, v10
	v_fma_f32 v13, -v9, v12, v11
	v_fmac_f32_e32 v12, v13, v10
	v_fma_f32 v9, -v9, v12, v11
	v_div_fmas_f32 v9, v9, v10, v12
	v_div_fixup_f32 v7, v9, v7, v8
	v_cndmask_b32_e64 v7, v7, -v7, s[38:39]
	v_add_f32_e32 v7, 1.0, v7
	v_mul_f32_e32 v6, v6, v7
	v_cvt_pk_bf16_f32 v6, v6, s0
	global_store_short v[2:3], v6, off offset:1024
	v_and_b32_e32 v7, 0xffff0000, v112
	v_lshlrev_b32_e32 v6, 16, v112
	v_pk_fma_f32 v[4:5], v[82:83], v[6:7], v[4:5]
	s_nop 0
	v_pk_mul_f32 v[6:7], v[4:5], s[28:29] op_sel_hi:[1,0]
	v_mul_f32_e32 v8, 0.5, v4
	v_pk_mul_f32 v[6:7], v[4:5], v[6:7]
	s_nop 0
	v_pk_fma_f32 v[6:7], v[4:5], v[6:7], v[4:5]
	s_nop 0
	v_pk_mul_f32 v[6:7], v[6:7], s[20:21] op_sel_hi:[1,0]
	s_nop 0
	v_mul_f32_e64 v4, |v6|, -2.0
	v_mul_f32_e32 v4, 0x3fb8aa3b, v4
	v_exp_f32_e32 v4, v4
	v_cmp_gt_f32_e64 s[38:39], 0, v7
	v_sub_f32_e32 v9, 1.0, v4
	v_add_f32_e32 v4, 1.0, v4
	v_div_scale_f32 v10, s[6:7], v4, v4, v9
	v_rcp_f32_e32 v11, v10
	s_nop 0
	v_fma_f32 v12, -v10, v11, 1.0
	v_fmac_f32_e32 v11, v12, v11
	v_div_scale_f32 v12, vcc, v9, v4, v9
	v_mul_f32_e32 v13, v12, v11
	v_fma_f32 v14, -v10, v13, v12
	v_fmac_f32_e32 v13, v14, v11
	v_fma_f32 v10, -v10, v13, v12
	v_div_fmas_f32 v10, v10, v11, v13
	v_div_fixup_f32 v4, v10, v4, v9
	v_cmp_gt_f32_e32 vcc, 0, v6
	s_nop 1
	v_cndmask_b32_e64 v4, v4, -v4, vcc
	v_add_f32_e32 v4, 1.0, v4
	v_mul_f32_e32 v4, v8, v4
	v_cvt_pk_bf16_f32 v4, v4, s0
	global_store_short v[2:3], v4, off offset:2048
	v_mul_f32_e32 v4, 0.5, v5
	v_mul_f32_e64 v5, |v7|, -2.0
	v_mul_f32_e32 v5, 0x3fb8aa3b, v5
	v_exp_f32_e32 v5, v5
	s_nop 0
	v_sub_f32_e32 v6, 1.0, v5
	v_add_f32_e32 v5, 1.0, v5
	v_div_scale_f32 v7, s[6:7], v5, v5, v6
	v_rcp_f32_e32 v8, v7
	s_nop 0
	v_fma_f32 v9, -v7, v8, 1.0
	v_fmac_f32_e32 v8, v9, v8
	v_div_scale_f32 v9, vcc, v6, v5, v6
	v_mul_f32_e32 v10, v9, v8
	v_fma_f32 v11, -v7, v10, v9
	v_fmac_f32_e32 v10, v11, v8
	v_fma_f32 v7, -v7, v10, v9
	v_div_fmas_f32 v7, v7, v8, v10
	v_div_fixup_f32 v5, v7, v5, v6
	v_cndmask_b32_e64 v5, v5, -v5, s[38:39]
	v_add_f32_e32 v5, 1.0, v5
	v_mul_f32_e32 v4, v4, v5
	v_cvt_pk_bf16_f32 v4, v4, s0
	global_store_short v[2:3], v4, off offset:3072
	s_barrier
	global_load_dwordx4 v[70:73], v[30:31], off
	global_load_ushort v228, v[28:29], off
	global_load_ushort v229, v[28:29], off offset:1024
	global_load_ushort v230, v[28:29], off offset:2048
	global_load_ushort v231, v[28:29], off offset:3072
	v_add_co_u32_e32 v2, vcc, s70, v28
	s_nop 1
	v_addc_co_u32_e32 v3, vcc, 0, v29, vcc
	global_load_ushort v232, v[2:3], off
	global_load_ushort v233, v[2:3], off offset:1024
	global_load_ushort v234, v[2:3], off offset:2048
	s_nop 0
	global_load_ushort v235, v[2:3], off offset:3072
	ds_read_b128 v[18:21], v104 offset:37888
	s_waitcnt lgkmcnt(0)
	v_mfma_f32_32x32x16_bf16 v[18:33], v[74:77], v[18:21], 0
	ds_read_b128 v[2:5], v104 offset:34816
	s_waitcnt lgkmcnt(0)
	v_mfma_f32_32x32x16_bf16 v[34:49], v[74:77], v[2:5], 0
	ds_read_b128 v[2:5], v104 offset:35840
	s_waitcnt lgkmcnt(0)
	v_mfma_f32_32x32x16_bf16 v[50:65], v[74:77], v[2:5], 0
	ds_read_b128 v[2:5], v104 offset:36864
	s_waitcnt lgkmcnt(0)
	v_mfma_f32_32x32x16_bf16 v[2:17], v[74:77], v[2:5], 0
	s_nop 9
	v_fmac_f32_e32 v34, v240, v237
	v_fmac_f32_e32 v50, v79, v236
	v_fmac_f32_e32 v2, v241, v239
	v_fmac_f32_e32 v18, v81, v238
	v_fmac_f32_e32 v34, v78, v236
	v_fmac_f32_e32 v50, v78, v237
	v_fmac_f32_e32 v2, v80, v238
	v_fmac_f32_e32 v18, v80, v239
	v_cvt_pk_bf16_f32 v242, v34, v50
	v_cvt_pk_bf16_f32 v243, v2, v18
	ds_write2_b32 v105, v242, v243 offset1:32
	v_fmac_f32_e32 v35, v240, v50
	v_fmac_f32_e32 v51, v79, v34
	v_fmac_f32_e32 v3, v241, v18
	v_fmac_f32_e32 v19, v81, v2
	v_fmac_f32_e32 v35, v78, v34
	v_fmac_f32_e32 v51, v78, v50
	v_fmac_f32_e32 v3, v80, v2
	v_fmac_f32_e32 v19, v80, v18
	v_cvt_pk_bf16_f32 v244, v35, v51
	v_cvt_pk_bf16_f32 v245, v3, v19
	ds_write2_b32 v105, v244, v245 offset0:68 offset1:100
	v_fmac_f32_e32 v36, v240, v51
	v_fmac_f32_e32 v52, v79, v35
	v_fmac_f32_e32 v4, v241, v19
	v_fmac_f32_e32 v20, v81, v3
	v_fmac_f32_e32 v36, v78, v35
	v_fmac_f32_e32 v52, v78, v51
	v_fmac_f32_e32 v4, v80, v3
	v_fmac_f32_e32 v20, v80, v19
	v_cvt_pk_bf16_f32 v242, v36, v52
	v_cvt_pk_bf16_f32 v243, v4, v20
	ds_write2_b32 v105, v242, v243 offset0:136 offset1:168
	v_fmac_f32_e32 v37, v240, v52
	v_fmac_f32_e32 v53, v79, v36
	v_fmac_f32_e32 v5, v241, v20
	v_fmac_f32_e32 v21, v81, v4
	v_fmac_f32_e32 v37, v78, v36
	v_fmac_f32_e32 v53, v78, v52
	v_fmac_f32_e32 v5, v80, v4
	v_fmac_f32_e32 v21, v80, v20
	v_cvt_pk_bf16_f32 v244, v37, v53
	v_cvt_pk_bf16_f32 v245, v5, v21
	ds_write2_b32 v105, v244, v245 offset0:204 offset1:236
	v_fmac_f32_e32 v38, v240, v53
	v_fmac_f32_e32 v54, v79, v37
	v_fmac_f32_e32 v6, v241, v21
	v_fmac_f32_e32 v22, v81, v5
	v_fmac_f32_e32 v38, v78, v37
	v_fmac_f32_e32 v54, v78, v53
	v_fmac_f32_e32 v6, v80, v5
	v_fmac_f32_e32 v22, v80, v21
	v_cvt_pk_bf16_f32 v242, v38, v54
	v_cvt_pk_bf16_f32 v243, v6, v22
	ds_write2_b32 v98, v242, v243 offset0:16 offset1:48
	v_fmac_f32_e32 v39, v240, v54
	v_fmac_f32_e32 v55, v79, v38
	v_fmac_f32_e32 v7, v241, v22
	v_fmac_f32_e32 v23, v81, v6
	v_fmac_f32_e32 v39, v78, v38
	v_fmac_f32_e32 v55, v78, v54
	v_fmac_f32_e32 v7, v80, v6
	v_fmac_f32_e32 v23, v80, v22
	v_cvt_pk_bf16_f32 v244, v39, v55
	v_cvt_pk_bf16_f32 v245, v7, v23
	ds_write2_b32 v98, v244, v245 offset0:84 offset1:116
	v_fmac_f32_e32 v40, v240, v55
	v_fmac_f32_e32 v56, v79, v39
	v_fmac_f32_e32 v8, v241, v23
	v_fmac_f32_e32 v24, v81, v7
	v_fmac_f32_e32 v40, v78, v39
	v_fmac_f32_e32 v56, v78, v55
	v_fmac_f32_e32 v8, v80, v7
	v_fmac_f32_e32 v24, v80, v23
	v_cvt_pk_bf16_f32 v242, v40, v56
	v_cvt_pk_bf16_f32 v243, v8, v24
	ds_write2_b32 v98, v242, v243 offset0:152 offset1:184
	v_fmac_f32_e32 v41, v240, v56
	v_fmac_f32_e32 v57, v79, v40
	v_fmac_f32_e32 v9, v241, v24
	v_fmac_f32_e32 v25, v81, v8
	v_fmac_f32_e32 v41, v78, v40
	v_fmac_f32_e32 v57, v78, v56
	v_fmac_f32_e32 v9, v80, v8
	v_fmac_f32_e32 v25, v80, v24
	v_cvt_pk_bf16_f32 v244, v41, v57
	v_cvt_pk_bf16_f32 v245, v9, v25
	ds_write2_b32 v98, v244, v245 offset0:220 offset1:252
	v_fmac_f32_e32 v42, v240, v57
	v_fmac_f32_e32 v58, v79, v41
	v_fmac_f32_e32 v10, v241, v25
	v_fmac_f32_e32 v26, v81, v9
	v_fmac_f32_e32 v42, v78, v41
	v_fmac_f32_e32 v58, v78, v57
	v_fmac_f32_e32 v10, v80, v9
	v_fmac_f32_e32 v26, v80, v25
	v_cvt_pk_bf16_f32 v242, v42, v58
	v_cvt_pk_bf16_f32 v243, v10, v26
	ds_write2_b32 v99, v242, v243 offset0:32 offset1:64
	v_fmac_f32_e32 v43, v240, v58
	v_fmac_f32_e32 v59, v79, v42
	v_fmac_f32_e32 v11, v241, v26
	v_fmac_f32_e32 v27, v81, v10
	v_fmac_f32_e32 v43, v78, v42
	v_fmac_f32_e32 v59, v78, v58
	v_fmac_f32_e32 v11, v80, v10
	v_fmac_f32_e32 v27, v80, v26
	v_cvt_pk_bf16_f32 v244, v43, v59
	v_cvt_pk_bf16_f32 v245, v11, v27
	ds_write2_b32 v99, v244, v245 offset0:100 offset1:132
	v_fmac_f32_e32 v44, v240, v59
	v_fmac_f32_e32 v60, v79, v43
	v_fmac_f32_e32 v12, v241, v27
	v_fmac_f32_e32 v28, v81, v11
	v_fmac_f32_e32 v44, v78, v43
	v_fmac_f32_e32 v60, v78, v59
	v_fmac_f32_e32 v12, v80, v11
	v_fmac_f32_e32 v28, v80, v27
	v_cvt_pk_bf16_f32 v242, v44, v60
	v_cvt_pk_bf16_f32 v243, v12, v28
	ds_write2_b32 v99, v242, v243 offset0:168 offset1:200
	v_fmac_f32_e32 v45, v240, v60
	v_fmac_f32_e32 v61, v79, v44
	v_fmac_f32_e32 v13, v241, v28
	v_fmac_f32_e32 v29, v81, v12
	v_fmac_f32_e32 v45, v78, v44
	v_fmac_f32_e32 v61, v78, v60
	v_fmac_f32_e32 v13, v80, v12
	v_fmac_f32_e32 v29, v80, v28
	v_cvt_pk_bf16_f32 v244, v45, v61
	v_cvt_pk_bf16_f32 v245, v13, v29
	ds_write2_b32 v124, v244, v245 offset0:108 offset1:140
	v_fmac_f32_e32 v46, v240, v61
	v_fmac_f32_e32 v62, v79, v45
	v_fmac_f32_e32 v14, v241, v29
	v_fmac_f32_e32 v30, v81, v13
	v_fmac_f32_e32 v46, v78, v45
	v_fmac_f32_e32 v62, v78, v61
	v_fmac_f32_e32 v14, v80, v13
	v_fmac_f32_e32 v30, v80, v29
	v_cvt_pk_bf16_f32 v242, v46, v62
	v_cvt_pk_bf16_f32 v243, v14, v30
	ds_write2_b32 v125, v242, v243 offset0:48 offset1:80
	v_fmac_f32_e32 v47, v240, v62
	v_fmac_f32_e32 v63, v79, v46
	v_fmac_f32_e32 v15, v241, v30
	v_fmac_f32_e32 v31, v81, v14
	v_fmac_f32_e32 v47, v78, v46
	v_fmac_f32_e32 v63, v78, v62
	v_fmac_f32_e32 v15, v80, v14
	v_fmac_f32_e32 v31, v80, v30
	v_cvt_pk_bf16_f32 v244, v47, v63
	v_cvt_pk_bf16_f32 v245, v15, v31
	ds_write2_b32 v125, v244, v245 offset0:116 offset1:148
	v_fmac_f32_e32 v48, v240, v63
	v_fmac_f32_e32 v64, v79, v47
	v_fmac_f32_e32 v16, v241, v31
	v_fmac_f32_e32 v32, v81, v15
	v_fmac_f32_e32 v48, v78, v47
	v_fmac_f32_e32 v64, v78, v63
	v_fmac_f32_e32 v16, v80, v15
	v_fmac_f32_e32 v32, v80, v31
	v_cvt_pk_bf16_f32 v242, v48, v64
	v_cvt_pk_bf16_f32 v243, v16, v32
	ds_write2_b32 v125, v242, v243 offset0:184 offset1:216
	v_fmac_f32_e32 v49, v240, v64
	v_fmac_f32_e32 v65, v79, v48
	v_fmac_f32_e32 v17, v241, v32
	v_fmac_f32_e32 v33, v81, v16
	v_fmac_f32_e32 v49, v78, v48
	v_fmac_f32_e32 v65, v78, v64
	v_fmac_f32_e32 v17, v80, v16
	v_fmac_f32_e32 v33, v80, v32
	v_cvt_pk_bf16_f32 v244, v49, v65
	v_cvt_pk_bf16_f32 v245, v17, v33
	ds_write2_b32 v126, v244, v245 offset0:124 offset1:156
	v_mov_b32_e32 v236, v49
	v_mov_b32_e32 v237, v65
	v_mov_b32_e32 v238, v17
	v_mov_b32_e32 v239, v33
	s_waitcnt lgkmcnt(0)
	s_barrier
	ds_read_b128 v[2:5], v106
	ds_read_b64 v[16:17], v104 offset:38912
	ds_read_b32 v14, v104 offset:38912
	ds_read2_b64 v[6:9], v127 offset0:1 offset1:128
	s_waitcnt vmcnt(0)
	v_perm_b32 v120, v229, v228, s69
	v_perm_b32 v121, v231, v230, s69
	v_perm_b32 v122, v233, v232, s69
	v_perm_b32 v123, v235, v234, s69
	v_mov_b64_e32 v[50:51], v[66:67]
	v_mov_b64_e32 v[76:77], v[72:73]
	v_mov_b32_e32 v112, v119
	v_mov_b32_e32 v113, v118
	s_waitcnt lgkmcnt(0)
	v_mov_b32_e32 v18, v6
	v_mov_b32_e32 v19, v7
	v_mov_b32_e32 v22, v8
	v_mov_b32_e32 v23, v9
	v_mfma_f32_16x16x32_bf16 v[10:13], v[2:5], v[16:19], 0
	ds_read_b128 v[18:21], v106 offset:64
	ds_read2_b64 v[2:5], v128 offset0:1 offset1:128
	v_mov_b64_e32 v[52:53], v[68:69]
	v_mov_b64_e32 v[74:75], v[70:71]
	s_waitcnt lgkmcnt(0)
	v_mov_b32_e32 v24, v2
	v_mov_b32_e32 v25, v3
	v_mov_b32_e32 v26, v4
	v_mov_b32_e32 v27, v5
	v_mfma_f32_16x16x32_bf16 v[18:21], v[18:21], v[22:25], v[10:13]
	ds_read_b128 v[22:25], v106 offset:128
	s_nop 1
	ds_read2_b64 v[10:13], v129 offset0:1 offset1:128
	s_waitcnt lgkmcnt(0)
	v_mov_b32_e32 v28, v10
	v_mov_b32_e32 v29, v11
	s_nop 1
	v_mfma_f32_16x16x32_bf16 v[22:25], v[22:25], v[26:29], v[18:21]
	ds_read_b128 v[26:29], v106 offset:192
	s_nop 1
	ds_read_b64 v[20:21], v104 offset:41992
	v_mov_b32_e32 v18, v12
	v_mov_b32_e32 v19, v13
	s_waitcnt lgkmcnt(0)
	s_nop 0
	v_mfma_f32_16x16x32_bf16 v[22:25], v[26:29], v[18:21], v[22:25]
	v_and_b32_e32 v19, 0xffff0000, v111
	v_lshlrev_b32_e32 v18, 16, v111
	v_mov_b32_e32 v111, v120
	s_nop 4
	v_pk_fma_f32 v[22:23], v[82:83], v[18:19], v[22:23]
	s_nop 0
	v_pk_mul_f32 v[18:19], v[22:23], s[28:29] op_sel_hi:[1,0]
	v_mul_f32_e32 v4, 0.5, v22
	v_pk_mul_f32 v[18:19], v[22:23], v[18:19]
	s_nop 0
	v_pk_fma_f32 v[18:19], v[22:23], v[18:19], v[22:23]
	s_nop 0
	v_pk_mul_f32 v[26:27], v[18:19], s[20:21] op_sel_hi:[1,0]
	s_nop 0
	v_mul_f32_e64 v8, |v26|, -2.0
	v_mul_f32_e32 v8, 0x3fb8aa3b, v8
	v_exp_f32_e32 v8, v8
	v_cmp_gt_f32_e64 s[38:39], 0, v27
	v_sub_f32_e32 v12, 1.0, v8
	v_add_f32_e32 v8, 1.0, v8
	v_div_scale_f32 v15, s[6:7], v8, v8, v12
	v_rcp_f32_e32 v16, v15
	s_nop 0
	v_fma_f32 v18, -v15, v16, 1.0
	v_fmac_f32_e32 v16, v18, v16
	v_div_scale_f32 v18, vcc, v12, v8, v12
	v_mul_f32_e32 v19, v18, v16
	v_fma_f32 v22, -v15, v19, v18
	v_fmac_f32_e32 v19, v22, v16
	v_fma_f32 v15, -v15, v19, v18
	v_div_fmas_f32 v15, v15, v16, v19
	v_div_fixup_f32 v8, v15, v8, v12
	v_cmp_gt_f32_e32 vcc, 0, v26
	s_nop 1
	v_cndmask_b32_e64 v8, v8, -v8, vcc
	v_add_f32_e32 v8, 1.0, v8
	v_mul_f32_e32 v4, v4, v8
	v_mul_f32_e64 v8, |v27|, -2.0
	v_mul_f32_e32 v8, 0x3fb8aa3b, v8
	v_exp_f32_e32 v8, v8
	v_add_co_u32_e32 v18, vcc, s72, v102
	v_cvt_pk_bf16_f32 v4, v4, s0
	v_sub_f32_e32 v12, 1.0, v8
	v_add_f32_e32 v8, 1.0, v8
	v_div_scale_f32 v15, s[6:7], v8, v8, v12
	v_rcp_f32_e32 v16, v15
	v_addc_co_u32_e32 v19, vcc, 0, v103, vcc
	global_store_short v[18:19], v4, off
	v_fma_f32 v22, -v15, v16, 1.0
	v_fmac_f32_e32 v16, v22, v16
	v_div_scale_f32 v22, vcc, v12, v8, v12
	v_mul_f32_e32 v4, 0.5, v23
	v_mul_f32_e32 v23, v22, v16
	v_fma_f32 v26, -v15, v23, v22
	v_fmac_f32_e32 v23, v26, v16
	v_fma_f32 v15, -v15, v23, v22
	v_div_fmas_f32 v15, v15, v16, v23
	v_and_b32_e32 v23, 0xffff0000, v110
	v_lshlrev_b32_e32 v22, 16, v110
	v_pk_fma_f32 v[22:23], v[82:83], v[22:23], v[24:25]
	v_div_fixup_f32 v8, v15, v8, v12
	v_pk_mul_f32 v[24:25], v[22:23], s[28:29] op_sel_hi:[1,0]
	v_cndmask_b32_e64 v8, v8, -v8, s[38:39]
	v_pk_mul_f32 v[24:25], v[22:23], v[24:25]
	v_add_f32_e32 v8, 1.0, v8
	v_pk_fma_f32 v[24:25], v[22:23], v[24:25], v[22:23]
	v_mul_f32_e32 v4, v4, v8
	v_pk_mul_f32 v[24:25], v[24:25], s[20:21] op_sel_hi:[1,0]
	v_cvt_pk_bf16_f32 v4, v4, s0
	v_mul_f32_e64 v8, |v24|, -2.0
	v_mul_f32_e32 v8, 0x3fb8aa3b, v8
	v_exp_f32_e32 v8, v8
	global_store_short v[18:19], v4, off offset:1024
	v_mul_f32_e32 v4, 0.5, v22
	v_cmp_gt_f32_e64 s[38:39], 0, v25
	v_sub_f32_e32 v12, 1.0, v8
	v_add_f32_e32 v8, 1.0, v8
	v_div_scale_f32 v15, s[6:7], v8, v8, v12
	v_rcp_f32_e32 v16, v15
	v_mov_b32_e32 v110, v121
	v_fma_f32 v22, -v15, v16, 1.0
	v_fmac_f32_e32 v16, v22, v16
	v_div_scale_f32 v22, vcc, v12, v8, v12
	v_mul_f32_e32 v26, v22, v16
	v_fma_f32 v27, -v15, v26, v22
	v_fmac_f32_e32 v26, v27, v16
	v_fma_f32 v15, -v15, v26, v22
	v_div_fmas_f32 v15, v15, v16, v26
	v_div_fixup_f32 v8, v15, v8, v12
	v_cmp_gt_f32_e32 vcc, 0, v24
	s_nop 1
	v_cndmask_b32_e64 v8, v8, -v8, vcc
	v_add_f32_e32 v8, 1.0, v8
	v_mul_f32_e32 v4, v4, v8
	v_mul_f32_e64 v8, |v25|, -2.0
	v_mul_f32_e32 v8, 0x3fb8aa3b, v8
	v_exp_f32_e32 v8, v8
	v_cvt_pk_bf16_f32 v4, v4, s0
	global_store_short v[18:19], v4, off offset:2048
	v_mul_f32_e32 v4, 0.5, v23
	v_sub_f32_e32 v12, 1.0, v8
	v_add_f32_e32 v8, 1.0, v8
	v_div_scale_f32 v15, s[6:7], v8, v8, v12
	v_rcp_f32_e32 v16, v15
	s_nop 0
	v_fma_f32 v22, -v15, v16, 1.0
	v_fmac_f32_e32 v16, v22, v16
	v_div_scale_f32 v22, vcc, v12, v8, v12
	v_mul_f32_e32 v23, v22, v16
	v_fma_f32 v24, -v15, v23, v22
	v_fmac_f32_e32 v23, v24, v16
	v_fma_f32 v15, -v15, v23, v22
	v_div_fmas_f32 v15, v15, v16, v23
	ds_read_b128 v[22:25], v107 offset:4352
	v_div_fixup_f32 v8, v15, v8, v12
	v_cndmask_b32_e64 v8, v8, -v8, s[38:39]
	v_add_f32_e32 v8, 1.0, v8
	v_mul_f32_e32 v4, v4, v8
	v_cvt_pk_bf16_f32 v4, v4, s0
	global_store_short v[18:19], v4, off offset:3072
	v_mov_b32_e32 v15, v17
	v_mov_b32_e32 v16, v6
	v_mov_b32_e32 v17, v7
	v_mov_b32_e32 v7, v9
	v_mov_b32_e32 v8, v2
	s_waitcnt lgkmcnt(0)
	v_mfma_f32_16x16x32_bf16 v[14:17], v[22:25], v[14:17], 0
	ds_read_b128 v[22:25], v107 offset:4416
	ds_read_b32 v6, v104 offset:39936
	v_mov_b32_e32 v9, v3
	v_mov_b32_e32 v3, v5
	v_mov_b32_e32 v4, v10
	s_waitcnt lgkmcnt(0)
	v_mfma_f32_16x16x32_bf16 v[6:9], v[22:25], v[6:9], v[14:17]
	s_nop 2
	ds_read_b128 v[14:17], v107 offset:4480
	ds_read_b32 v2, v104 offset:40960
	v_mov_b32_e32 v5, v11
	v_mov_b32_e32 v19, v13
	s_waitcnt lgkmcnt(0)
	v_mfma_f32_16x16x32_bf16 v[2:5], v[14:17], v[2:5], v[6:9]
	s_nop 2
	ds_read_b128 v[6:9], v107 offset:4544
	ds_read_b32 v18, v104 offset:41984
	s_waitcnt lgkmcnt(0)
	v_mfma_f32_16x16x32_bf16 v[2:5], v[6:9], v[18:21], v[2:5]
	v_and_b32_e32 v7, 0xffff0000, v109
	v_lshlrev_b32_e32 v6, 16, v109
	v_mov_b32_e32 v109, v122
	s_nop 4
	v_pk_fma_f32 v[6:7], v[82:83], v[6:7], v[2:3]
	s_nop 0
	v_pk_mul_f32 v[2:3], v[6:7], s[28:29] op_sel_hi:[1,0]
	v_mul_f32_e32 v10, 0.5, v6
	v_pk_mul_f32 v[2:3], v[6:7], v[2:3]
	s_nop 0
	v_pk_fma_f32 v[2:3], v[6:7], v[2:3], v[6:7]
	s_nop 0
	v_pk_mul_f32 v[8:9], v[2:3], s[20:21] op_sel_hi:[1,0]
	s_nop 0
	v_mul_f32_e64 v2, |v8|, -2.0
	v_mul_f32_e32 v2, 0x3fb8aa3b, v2
	v_exp_f32_e32 v2, v2
	v_cmp_gt_f32_e64 s[38:39], 0, v9
	v_sub_f32_e32 v3, 1.0, v2
	v_add_f32_e32 v2, 1.0, v2
	v_div_scale_f32 v6, s[6:7], v2, v2, v3
	v_rcp_f32_e32 v11, v6
	s_nop 0
	v_fma_f32 v12, -v6, v11, 1.0
	v_fmac_f32_e32 v11, v12, v11
	v_div_scale_f32 v12, vcc, v3, v2, v3
	v_mul_f32_e32 v13, v12, v11
	v_fma_f32 v14, -v6, v13, v12
	v_fmac_f32_e32 v13, v14, v11
	v_fma_f32 v6, -v6, v13, v12
	v_div_fmas_f32 v6, v6, v11, v13
	v_div_fixup_f32 v2, v6, v2, v3
	v_cmp_gt_f32_e32 vcc, 0, v8
	s_nop 1
	v_cndmask_b32_e64 v2, v2, -v2, vcc
	v_add_f32_e32 v2, 1.0, v2
	v_mul_f32_e32 v2, v10, v2
	v_cvt_pk_bf16_f32 v6, v2, s0
	v_add_co_u32_e32 v2, vcc, s72, v100
	s_nop 1
	v_addc_co_u32_e32 v3, vcc, 0, v101, vcc
	global_store_short v[2:3], v6, off
	v_mul_f32_e32 v6, 0.5, v7
	v_mul_f32_e64 v7, |v9|, -2.0
	v_mul_f32_e32 v7, 0x3fb8aa3b, v7
	v_exp_f32_e32 v7, v7
	s_nop 0
	v_sub_f32_e32 v8, 1.0, v7
	v_add_f32_e32 v7, 1.0, v7
	v_div_scale_f32 v9, s[6:7], v7, v7, v8
	v_rcp_f32_e32 v10, v9
	s_nop 0
	v_fma_f32 v11, -v9, v10, 1.0
	v_fmac_f32_e32 v10, v11, v10
	v_div_scale_f32 v11, vcc, v8, v7, v8
	v_mul_f32_e32 v12, v11, v10
	v_fma_f32 v13, -v9, v12, v11
	v_fmac_f32_e32 v12, v13, v10
	v_fma_f32 v9, -v9, v12, v11
	v_div_fmas_f32 v9, v9, v10, v12
	v_div_fixup_f32 v7, v9, v7, v8
	v_cndmask_b32_e64 v7, v7, -v7, s[38:39]
	v_add_f32_e32 v7, 1.0, v7
	v_mul_f32_e32 v6, v6, v7
	v_cvt_pk_bf16_f32 v6, v6, s0
	global_store_short v[2:3], v6, off offset:1024
	v_and_b32_e32 v7, 0xffff0000, v108
	v_lshlrev_b32_e32 v6, 16, v108
	v_pk_fma_f32 v[4:5], v[82:83], v[6:7], v[4:5]
	v_mov_b32_e32 v108, v123
	v_pk_mul_f32 v[6:7], v[4:5], s[28:29] op_sel_hi:[1,0]
	v_mul_f32_e32 v8, 0.5, v4
	v_pk_mul_f32 v[6:7], v[4:5], v[6:7]
	s_nop 0
	v_pk_fma_f32 v[6:7], v[4:5], v[6:7], v[4:5]
	s_nop 0
	v_pk_mul_f32 v[6:7], v[6:7], s[20:21] op_sel_hi:[1,0]
	s_nop 0
	v_mul_f32_e64 v4, |v6|, -2.0
	v_mul_f32_e32 v4, 0x3fb8aa3b, v4
	v_exp_f32_e32 v4, v4
	v_cmp_gt_f32_e64 s[38:39], 0, v7
	v_sub_f32_e32 v9, 1.0, v4
	v_add_f32_e32 v4, 1.0, v4
	v_div_scale_f32 v10, s[6:7], v4, v4, v9
	v_rcp_f32_e32 v11, v10
	s_nop 0
	v_fma_f32 v12, -v10, v11, 1.0
	v_fmac_f32_e32 v11, v12, v11
	v_div_scale_f32 v12, vcc, v9, v4, v9
	v_mul_f32_e32 v13, v12, v11
	v_fma_f32 v14, -v10, v13, v12
	v_fmac_f32_e32 v13, v14, v11
	v_fma_f32 v10, -v10, v13, v12
	v_div_fmas_f32 v10, v10, v11, v13
	v_div_fixup_f32 v4, v10, v4, v9
	v_cmp_gt_f32_e32 vcc, 0, v6
	s_nop 1
	v_cndmask_b32_e64 v4, v4, -v4, vcc
	v_add_f32_e32 v4, 1.0, v4
	v_mul_f32_e32 v4, v8, v4
	v_cvt_pk_bf16_f32 v4, v4, s0
	global_store_short v[2:3], v4, off offset:2048
	v_mul_f32_e32 v4, 0.5, v5
	v_mul_f32_e64 v5, |v7|, -2.0
	v_mul_f32_e32 v5, 0x3fb8aa3b, v5
	v_exp_f32_e32 v5, v5
	s_nop 0
	v_sub_f32_e32 v6, 1.0, v5
	v_add_f32_e32 v5, 1.0, v5
	v_div_scale_f32 v7, s[6:7], v5, v5, v6
	v_rcp_f32_e32 v8, v7
	s_nop 0
	v_fma_f32 v9, -v7, v8, 1.0
	v_fmac_f32_e32 v8, v9, v8
	v_div_scale_f32 v9, vcc, v6, v5, v6
	v_mul_f32_e32 v10, v9, v8
	v_fma_f32 v11, -v7, v10, v9
	v_fmac_f32_e32 v10, v11, v8
	v_fma_f32 v7, -v7, v10, v9
	v_div_fmas_f32 v7, v7, v8, v10
	v_div_fixup_f32 v5, v7, v5, v6
	v_cndmask_b32_e64 v5, v5, -v5, s[38:39]
	v_add_f32_e32 v5, 1.0, v5
	v_mul_f32_e32 v4, v4, v5
	v_cvt_pk_bf16_f32 v4, v4, s0
	global_store_short v[2:3], v4, off offset:3072
	s_barrier
	s_cbranch_scc1 .LBB0_178
	s_setprio 0
	v_mov_b32_e32 v0, v133
	s_barrier
	s_nop 0
	v_cmp_eq_u32_e32 vcc, 0, v0
	s_and_saveexec_b64 s[4:5], vcc
	s_cbranch_execnz .LBB0_173
	s_branch .LBB0_176
